# plus: rotate-tile epilogue drops redundant store-drain waits; state_unit loop uses counted vmcnt (15/15/13/8) instead of vmcnt(0) at loop head
# speedup vs baseline: 1.0256x; 1.0023x over previous
;     __device__ __forceinline__ void operator()(const pg8::f32x4 (&acc)[2][2][4][2], const pg8::Unit& u, int wr, int wc, int fr, int fq) const {
;     ...
;                 if (type == 1 || type == 2) {
;                     const float pos = (float)(row & 2047); const float sc = type == 2 ? 0.0625f : 1.f;
; #pragma unroll
;                     for (int e = 0; e < 8; ++e) { const float fx = __builtin_amdgcn_fractf(pos * (e < 4 ? rv0[e & 3] : rv1[e & 3]));
;                         const float c = __builtin_amdgcn_cosf(fx) * sc, s = __builtin_amdgcn_sinf(fx) * sc; const float x1 = a[e], x2 = b[e]; a[e] = x1 * c - x2 * s; b[e] = x2 * c + x1 * s; }
.LBB0_275:
	s_andn2_b64 vcc, exec, s[52:53]
	s_waitcnt lgkmcnt(0)
	v_and_b32_e32 v131, 0x7df, v122
	s_cbranch_vccnz .LBB0_277
	v_cvt_f32_u32_e32 v123, v131
	v_mul_f32_e32 v110, v24, v123
	v_fract_f32_e32 v111, v110
	v_cos_f32_e32 v110, v111
	v_sin_f32_e32 v112, v111
	v_mul_f32_e32 v111, v25, v123
	v_fract_f32_e32 v113, v111
	v_cos_f32_e32 v111, v113
	v_sin_f32_e32 v113, v113
	v_mul_f32_e32 v106, v22, v123
	v_fract_f32_e32 v107, v106
	v_pk_mul_f32 v[168:169], v[130:131], v[110:111] op_sel_hi:[0,1]
	v_pk_mul_f32 v[110:111], v[130:131], v[112:113] op_sel_hi:[0,1]
	v_pk_mul_f32 v[170:171], v[110:111], v[126:127]
	v_pk_mul_f32 v[112:113], v[110:111], v[120:121]
	v_mul_f32_e32 v110, v18, v123
	v_fract_f32_e32 v111, v110
	v_cos_f32_e32 v110, v111
	v_sin_f32_e32 v162, v111
	v_mul_f32_e32 v111, v19, v123
	v_fract_f32_e32 v135, v111
	v_cos_f32_e32 v111, v135
	v_sin_f32_e32 v163, v135
	v_cos_f32_e32 v106, v107
	v_sin_f32_e32 v108, v107
	v_pk_mul_f32 v[172:173], v[130:131], v[110:111] op_sel_hi:[0,1]
	v_pk_mul_f32 v[110:111], v[130:131], v[162:163] op_sel_hi:[0,1]
	v_pk_mul_f32 v[174:175], v[110:111], v[128:129]
	v_pk_mul_f32 v[162:163], v[110:111], v[114:115]
	v_mul_f32_e32 v110, v20, v123
	v_fract_f32_e32 v110, v110
	v_cos_f32_e32 v111, v110
	v_sin_f32_e32 v110, v110
	v_mul_f32_e32 v107, v23, v123
	v_fract_f32_e32 v109, v107
	v_mul_f32_e32 v111, v130, v111
	v_mul_f32_e32 v110, v130, v110
	v_mul_f32_e32 v164, v111, v134
	v_mul_f32_e32 v176, v110, v136
	v_mul_f32_e32 v134, v110, v134
	v_mul_f32_e32 v110, v21, v123
	v_mul_f32_e32 v136, v111, v136
	v_fract_f32_e32 v111, v110
	v_cos_f32_e32 v107, v109
	v_sin_f32_e32 v109, v109
	v_cos_f32_e32 v110, v111
	v_sin_f32_e32 v111, v111
	v_pk_mul_f32 v[106:107], v[130:131], v[106:107] op_sel_hi:[0,1]
	v_pk_mul_f32 v[108:109], v[130:131], v[108:109] op_sel_hi:[0,1]
	v_pk_mul_f32 v[166:167], v[108:109], v[124:125]
	v_pk_mul_f32 v[178:179], v[130:131], v[110:111] op_sel_hi:[0,1]
	v_pk_mul_f32 v[108:109], v[108:109], v[118:119]
	v_pk_mul_f32 v[110:111], v[178:179], v[132:133]
	v_pk_fma_f32 v[112:113], v[168:169], v[126:127], v[112:113] neg_lo:[0,0,1] neg_hi:[0,0,1]
	v_mov_b32_e32 v165, v110
	v_mov_b32_e32 v177, v111
	v_pk_fma_f32 v[110:111], v[106:107], v[124:125], v[108:109] neg_lo:[0,0,1] neg_hi:[0,0,1]
	v_pk_mul_f32 v[108:109], v[178:179], v[116:117]
	v_pk_fma_f32 v[162:163], v[172:173], v[128:129], v[162:163] neg_lo:[0,0,1] neg_hi:[0,0,1]
	v_mov_b32_e32 v137, v108
	v_mov_b32_e32 v135, v109
	v_pk_add_f32 v[164:165], v[164:165], v[176:177] neg_lo:[0,1] neg_hi:[0,1]
	v_pk_fma_f32 v[166:167], v[106:107], v[118:119], v[166:167]
	v_pk_fma_f32 v[168:169], v[168:169], v[120:121], v[170:171]
	v_pk_fma_f32 v[170:171], v[172:173], v[114:115], v[174:175]
	v_pk_add_f32 v[172:173], v[136:137], v[134:135]

;     __device__ __forceinline__ void operator()(const pg8::f32x4 (&acc)[2][2][4][2], const pg8::Unit& u, int wr, int wc, int fr, int fq) const {
;     ...
;                 if (type == 1 || type == 2) {
;                     const float pos = (float)(row & 2047); const float sc = type == 2 ? 0.0625f : 1.f;
; #pragma unroll
;                     for (int e = 0; e < 8; ++e) { const float fx = __builtin_amdgcn_fractf(pos * (e < 4 ? rv0[e & 3] : rv1[e & 3]));
;                         const float c = __builtin_amdgcn_cosf(fx) * sc, s = __builtin_amdgcn_sinf(fx) * sc; const float x1 = a[e], x2 = b[e]; a[e] = x1 * c - x2 * s; b[e] = x2 * c + x1 * s; }
.LBB0_302:
	s_andn2_b64 vcc, exec, s[50:51]
	v_and_b32_e32 v117, 0x7ef, v106
	s_cbranch_vccnz .LBB0_304
	v_cvt_f32_u32_e32 v107, v117
	v_mul_f32_e32 v94, v24, v107
	v_fract_f32_e32 v95, v94
	v_cos_f32_e32 v94, v95
	v_sin_f32_e32 v96, v95
	v_mul_f32_e32 v95, v25, v107
	v_fract_f32_e32 v97, v95
	v_cos_f32_e32 v95, v97
	v_sin_f32_e32 v97, v97
	v_mul_f32_e32 v90, v22, v107
	v_fract_f32_e32 v91, v90
	v_pk_mul_f32 v[126:127], v[130:131], v[94:95] op_sel_hi:[0,1]
	v_pk_mul_f32 v[94:95], v[130:131], v[96:97] op_sel_hi:[0,1]
	v_pk_mul_f32 v[128:129], v[94:95], v[110:111]
	v_pk_mul_f32 v[96:97], v[94:95], v[104:105]
	v_mul_f32_e32 v94, v18, v107
	v_fract_f32_e32 v95, v94
	v_cos_f32_e32 v94, v95
	v_sin_f32_e32 v120, v95
	v_mul_f32_e32 v95, v19, v107
	v_fract_f32_e32 v119, v95
	v_cos_f32_e32 v95, v119
	v_sin_f32_e32 v121, v119
	v_cos_f32_e32 v90, v91
	v_sin_f32_e32 v92, v91
	v_pk_mul_f32 v[132:133], v[130:131], v[94:95] op_sel_hi:[0,1]
	v_pk_mul_f32 v[94:95], v[130:131], v[120:121] op_sel_hi:[0,1]
	v_pk_mul_f32 v[134:135], v[94:95], v[112:113]
	v_pk_mul_f32 v[120:121], v[94:95], v[98:99]
	v_mul_f32_e32 v94, v20, v107
	v_fract_f32_e32 v94, v94
	v_cos_f32_e32 v95, v94
	v_sin_f32_e32 v94, v94
	v_mul_f32_e32 v91, v23, v107
	v_fract_f32_e32 v93, v91
	v_mul_f32_e32 v95, v130, v95
	v_mul_f32_e32 v94, v130, v94
	v_mul_f32_e32 v136, v94, v118
	v_mul_f32_e32 v162, v94, v116
	v_mul_f32_e32 v94, v21, v107
	v_mul_f32_e32 v122, v95, v116
	v_mul_f32_e32 v118, v95, v118
	v_fract_f32_e32 v95, v94
	v_cos_f32_e32 v91, v93
	v_sin_f32_e32 v93, v93
	v_cos_f32_e32 v94, v95
	v_sin_f32_e32 v95, v95
	v_pk_mul_f32 v[90:91], v[130:131], v[90:91] op_sel_hi:[0,1]
	v_pk_mul_f32 v[92:93], v[130:131], v[92:93] op_sel_hi:[0,1]
	v_pk_mul_f32 v[124:125], v[92:93], v[108:109]
	v_pk_mul_f32 v[164:165], v[130:131], v[94:95] op_sel_hi:[0,1]
	v_pk_mul_f32 v[92:93], v[92:93], v[102:103]
	v_pk_mul_f32 v[94:95], v[164:165], v[114:115]
	v_pk_fma_f32 v[96:97], v[126:127], v[110:111], v[96:97] neg_lo:[0,0,1] neg_hi:[0,0,1]
	v_mov_b32_e32 v123, v94
	v_mov_b32_e32 v137, v95
	v_pk_fma_f32 v[94:95], v[90:91], v[108:109], v[92:93] neg_lo:[0,0,1] neg_hi:[0,0,1]
	v_pk_mul_f32 v[92:93], v[164:165], v[100:101]
	v_pk_fma_f32 v[120:121], v[132:133], v[112:113], v[120:121] neg_lo:[0,0,1] neg_hi:[0,0,1]
	v_mov_b32_e32 v119, v92
	v_mov_b32_e32 v163, v93
	v_pk_add_f32 v[122:123], v[122:123], v[136:137] neg_lo:[0,1] neg_hi:[0,1]
	v_pk_fma_f32 v[124:125], v[90:91], v[102:103], v[124:125]
	v_pk_fma_f32 v[126:127], v[126:127], v[104:105], v[128:129]
	v_pk_fma_f32 v[128:129], v[132:133], v[98:99], v[134:135]
	v_pk_add_f32 v[132:133], v[118:119], v[162:163]

;     __device__ __forceinline__ void operator()(const pg8::f32x4 (&acc)[2][2][4][2], const pg8::Unit& u, int wr, int wc, int fr, int fq) const {
;     ...
;                 if (type == 1 || type == 2) {
;                     const float pos = (float)(row & 2047); const float sc = type == 2 ? 0.0625f : 1.f;
; #pragma unroll
;                     for (int e = 0; e < 8; ++e) { const float fx = __builtin_amdgcn_fractf(pos * (e < 4 ? rv0[e & 3] : rv1[e & 3]));
;                         const float c = __builtin_amdgcn_cosf(fx) * sc, s = __builtin_amdgcn_sinf(fx) * sc; const float x1 = a[e], x2 = b[e]; a[e] = x1 * c - x2 * s; b[e] = x2 * c + x1 * s; }
.LBB0_329:
	s_andn2_b64 vcc, exec, s[50:51]
	v_and_b32_e32 v101, 0x7ff, v90
	s_cbranch_vccnz .LBB0_331
	v_cvt_f32_u32_e32 v91, v101
	v_mul_f32_e32 v78, v24, v91
	v_fract_f32_e32 v79, v78
	v_cos_f32_e32 v78, v79
	v_sin_f32_e32 v80, v79
	v_mul_f32_e32 v79, v25, v91
	v_fract_f32_e32 v81, v79
	v_cos_f32_e32 v79, v81
	v_sin_f32_e32 v81, v81
	v_mul_f32_e32 v74, v22, v91
	v_fract_f32_e32 v75, v74
	v_pk_mul_f32 v[110:111], v[130:131], v[78:79] op_sel_hi:[0,1]
	v_pk_mul_f32 v[78:79], v[130:131], v[80:81] op_sel_hi:[0,1]
	v_pk_mul_f32 v[112:113], v[78:79], v[94:95]
	v_pk_mul_f32 v[80:81], v[78:79], v[88:89]
	v_mul_f32_e32 v78, v18, v91
	v_fract_f32_e32 v79, v78
	v_cos_f32_e32 v78, v79
	v_sin_f32_e32 v104, v79
	v_mul_f32_e32 v79, v19, v91
	v_fract_f32_e32 v103, v79
	v_cos_f32_e32 v79, v103
	v_sin_f32_e32 v105, v103
	v_cos_f32_e32 v74, v75
	v_sin_f32_e32 v76, v75
	v_pk_mul_f32 v[114:115], v[130:131], v[78:79] op_sel_hi:[0,1]
	v_pk_mul_f32 v[78:79], v[130:131], v[104:105] op_sel_hi:[0,1]
	v_pk_mul_f32 v[116:117], v[78:79], v[96:97]
	v_pk_mul_f32 v[104:105], v[78:79], v[82:83]
	v_mul_f32_e32 v78, v20, v91
	v_fract_f32_e32 v78, v78
	v_cos_f32_e32 v79, v78
	v_sin_f32_e32 v78, v78
	v_mul_f32_e32 v75, v23, v91
	v_fract_f32_e32 v77, v75
	v_mul_f32_e32 v79, v130, v79
	v_mul_f32_e32 v78, v130, v78
	v_mul_f32_e32 v118, v78, v102
	v_mul_f32_e32 v120, v78, v100
	v_mul_f32_e32 v78, v21, v91
	v_mul_f32_e32 v106, v79, v100
	v_mul_f32_e32 v102, v79, v102
	v_fract_f32_e32 v79, v78
	v_cos_f32_e32 v75, v77
	v_sin_f32_e32 v77, v77
	v_cos_f32_e32 v78, v79
	v_sin_f32_e32 v79, v79
	v_pk_mul_f32 v[74:75], v[130:131], v[74:75] op_sel_hi:[0,1]
	v_pk_mul_f32 v[76:77], v[130:131], v[76:77] op_sel_hi:[0,1]
	v_pk_mul_f32 v[108:109], v[76:77], v[92:93]
	v_pk_mul_f32 v[122:123], v[130:131], v[78:79] op_sel_hi:[0,1]
	v_pk_mul_f32 v[76:77], v[76:77], v[86:87]
	v_pk_mul_f32 v[78:79], v[122:123], v[98:99]
	v_pk_fma_f32 v[80:81], v[110:111], v[94:95], v[80:81] neg_lo:[0,0,1] neg_hi:[0,0,1]
	v_mov_b32_e32 v107, v78
	v_mov_b32_e32 v119, v79
	v_pk_fma_f32 v[78:79], v[74:75], v[92:93], v[76:77] neg_lo:[0,0,1] neg_hi:[0,0,1]
	v_pk_mul_f32 v[76:77], v[122:123], v[84:85]
	v_pk_fma_f32 v[104:105], v[114:115], v[96:97], v[104:105] neg_lo:[0,0,1] neg_hi:[0,0,1]
	v_mov_b32_e32 v103, v76
	v_mov_b32_e32 v121, v77
	v_pk_add_f32 v[106:107], v[106:107], v[118:119] neg_lo:[0,1] neg_hi:[0,1]
	v_pk_fma_f32 v[108:109], v[74:75], v[86:87], v[108:109]
	v_pk_fma_f32 v[110:111], v[110:111], v[88:89], v[112:113]
	v_pk_fma_f32 v[112:113], v[114:115], v[82:83], v[116:117]
	v_pk_add_f32 v[114:115], v[102:103], v[120:121]

;     __device__ __forceinline__ void operator()(const pg8::f32x4 (&acc)[2][2][4][2], const pg8::Unit& u, int wr, int wc, int fr, int fq) const {
;     ...
;                 if (type == 1 || type == 2) {
;                     const float pos = (float)(row & 2047); const float sc = type == 2 ? 0.0625f : 1.f;
; #pragma unroll
;                     for (int e = 0; e < 8; ++e) { const float fx = __builtin_amdgcn_fractf(pos * (e < 4 ? rv0[e & 3] : rv1[e & 3]));
;                         const float c = __builtin_amdgcn_cosf(fx) * sc, s = __builtin_amdgcn_sinf(fx) * sc; const float x1 = a[e], x2 = b[e]; a[e] = x1 * c - x2 * s; b[e] = x2 * c + x1 * s; }
.LBB0_356:
	s_andn2_b64 vcc, exec, s[50:51]
	s_cbranch_vccnz .LBB0_358
	v_and_b32_e32 v58, 0x7cf, v74
	v_cvt_f32_u32_e32 v75, v58
	v_mul_f32_e32 v62, v24, v75
	v_fract_f32_e32 v63, v62
	v_cos_f32_e32 v62, v63
	v_sin_f32_e32 v64, v63
	v_mul_f32_e32 v63, v25, v75
	v_fract_f32_e32 v65, v63
	v_cos_f32_e32 v63, v65
	v_sin_f32_e32 v65, v65
	v_mul_f32_e32 v58, v22, v75
	v_fract_f32_e32 v59, v58
	v_pk_mul_f32 v[94:95], v[130:131], v[62:63] op_sel_hi:[0,1]
	v_pk_mul_f32 v[62:63], v[130:131], v[64:65] op_sel_hi:[0,1]
	v_pk_mul_f32 v[96:97], v[62:63], v[78:79]
	v_pk_mul_f32 v[64:65], v[62:63], v[72:73]
	v_mul_f32_e32 v62, v18, v75
	v_fract_f32_e32 v63, v62
	v_cos_f32_e32 v62, v63
	v_sin_f32_e32 v88, v63
	v_mul_f32_e32 v63, v19, v75
	v_fract_f32_e32 v85, v63
	v_cos_f32_e32 v63, v85
	v_sin_f32_e32 v89, v85
	v_cos_f32_e32 v58, v59
	v_sin_f32_e32 v60, v59
	v_pk_mul_f32 v[98:99], v[130:131], v[62:63] op_sel_hi:[0,1]
	v_pk_mul_f32 v[62:63], v[130:131], v[88:89] op_sel_hi:[0,1]
	v_pk_mul_f32 v[100:101], v[62:63], v[80:81]
	v_pk_mul_f32 v[88:89], v[62:63], v[66:67]
	v_mul_f32_e32 v62, v20, v75
	v_fract_f32_e32 v62, v62
	v_cos_f32_e32 v63, v62
	v_sin_f32_e32 v62, v62
	v_mul_f32_e32 v59, v23, v75
	v_fract_f32_e32 v61, v59
	v_mul_f32_e32 v63, v130, v63
	v_mul_f32_e32 v62, v130, v62
	v_mul_f32_e32 v90, v63, v84
	v_mul_f32_e32 v102, v62, v86
	v_mul_f32_e32 v84, v62, v84
	v_mul_f32_e32 v62, v21, v75
	v_mul_f32_e32 v86, v63, v86
	v_fract_f32_e32 v63, v62
	v_cos_f32_e32 v59, v61
	v_sin_f32_e32 v61, v61
	v_cos_f32_e32 v62, v63
	v_sin_f32_e32 v63, v63
	v_pk_mul_f32 v[58:59], v[130:131], v[58:59] op_sel_hi:[0,1]
	v_pk_mul_f32 v[60:61], v[130:131], v[60:61] op_sel_hi:[0,1]
	v_pk_mul_f32 v[92:93], v[60:61], v[76:77]
	v_pk_mul_f32 v[104:105], v[130:131], v[62:63] op_sel_hi:[0,1]
	v_pk_mul_f32 v[60:61], v[60:61], v[70:71]
	v_pk_mul_f32 v[62:63], v[104:105], v[82:83]
	v_pk_fma_f32 v[64:65], v[94:95], v[78:79], v[64:65] neg_lo:[0,0,1] neg_hi:[0,0,1]
	v_mov_b32_e32 v91, v62
	v_mov_b32_e32 v103, v63
	v_pk_fma_f32 v[62:63], v[58:59], v[76:77], v[60:61] neg_lo:[0,0,1] neg_hi:[0,0,1]
	v_pk_mul_f32 v[60:61], v[104:105], v[68:69]
	v_pk_fma_f32 v[88:89], v[98:99], v[80:81], v[88:89] neg_lo:[0,0,1] neg_hi:[0,0,1]
	v_mov_b32_e32 v87, v60
	v_mov_b32_e32 v85, v61
	v_pk_add_f32 v[90:91], v[90:91], v[102:103] neg_lo:[0,1] neg_hi:[0,1]
	v_pk_fma_f32 v[92:93], v[58:59], v[70:71], v[92:93]
	v_pk_fma_f32 v[94:95], v[94:95], v[72:73], v[96:97]
	v_pk_fma_f32 v[96:97], v[98:99], v[66:67], v[100:101]
	v_pk_add_f32 v[98:99], v[86:87], v[84:85]

;     __device__ __forceinline__ void operator()(const pg8::f32x4 (&acc)[2][2][4][2], const pg8::Unit& u, int wr, int wc, int fr, int fq) const {
;     ...
;                 if (type == 1 || type == 2) {
;                     const float pos = (float)(row & 2047); const float sc = type == 2 ? 0.0625f : 1.f;
; #pragma unroll
;                     for (int e = 0; e < 8; ++e) { const float fx = __builtin_amdgcn_fractf(pos * (e < 4 ? rv0[e & 3] : rv1[e & 3]));
;                         const float c = __builtin_amdgcn_cosf(fx) * sc, s = __builtin_amdgcn_sinf(fx) * sc; const float x1 = a[e], x2 = b[e]; a[e] = x1 * c - x2 * s; b[e] = x2 * c + x1 * s; }
.LBB0_383:
	s_andn2_b64 vcc, exec, s[50:51]
	s_cbranch_vccnz .LBB0_385
	v_and_b32_e32 v42, 0x7df, v58
	v_cvt_f32_u32_e32 v59, v42
	v_mul_f32_e32 v46, v24, v59
	v_fract_f32_e32 v47, v46
	v_cos_f32_e32 v46, v47
	v_sin_f32_e32 v48, v47
	v_mul_f32_e32 v47, v25, v59
	v_fract_f32_e32 v49, v47
	v_cos_f32_e32 v47, v49
	v_sin_f32_e32 v49, v49
	v_mul_f32_e32 v42, v22, v59
	v_fract_f32_e32 v43, v42
	v_pk_mul_f32 v[78:79], v[130:131], v[46:47] op_sel_hi:[0,1]
	v_pk_mul_f32 v[46:47], v[130:131], v[48:49] op_sel_hi:[0,1]
	v_pk_mul_f32 v[80:81], v[46:47], v[62:63]
	v_pk_mul_f32 v[48:49], v[46:47], v[56:57]
	v_mul_f32_e32 v46, v18, v59
	v_fract_f32_e32 v47, v46
	v_cos_f32_e32 v46, v47
	v_sin_f32_e32 v72, v47
	v_mul_f32_e32 v47, v19, v59
	v_fract_f32_e32 v69, v47
	v_cos_f32_e32 v47, v69
	v_sin_f32_e32 v73, v69
	v_cos_f32_e32 v42, v43
	v_sin_f32_e32 v44, v43
	v_pk_mul_f32 v[82:83], v[130:131], v[46:47] op_sel_hi:[0,1]
	v_pk_mul_f32 v[46:47], v[130:131], v[72:73] op_sel_hi:[0,1]
	v_pk_mul_f32 v[86:87], v[46:47], v[64:65]
	v_pk_mul_f32 v[72:73], v[46:47], v[50:51]
	v_mul_f32_e32 v46, v20, v59
	v_fract_f32_e32 v46, v46
	v_cos_f32_e32 v47, v46
	v_sin_f32_e32 v46, v46
	v_mul_f32_e32 v43, v23, v59
	v_fract_f32_e32 v45, v43
	v_mul_f32_e32 v47, v130, v47
	v_mul_f32_e32 v46, v130, v46
	v_mul_f32_e32 v74, v47, v68
	v_mul_f32_e32 v88, v46, v70
	v_mul_f32_e32 v68, v46, v68
	v_mul_f32_e32 v46, v21, v59
	v_mul_f32_e32 v70, v47, v70
	v_fract_f32_e32 v47, v46
	v_cos_f32_e32 v43, v45
	v_sin_f32_e32 v45, v45
	v_cos_f32_e32 v46, v47
	v_sin_f32_e32 v47, v47
	v_pk_mul_f32 v[42:43], v[130:131], v[42:43] op_sel_hi:[0,1]
	v_pk_mul_f32 v[44:45], v[130:131], v[44:45] op_sel_hi:[0,1]
	v_pk_mul_f32 v[76:77], v[44:45], v[60:61]
	v_pk_mul_f32 v[90:91], v[130:131], v[46:47] op_sel_hi:[0,1]
	v_pk_mul_f32 v[44:45], v[44:45], v[54:55]
	v_pk_mul_f32 v[46:47], v[90:91], v[66:67]
	v_pk_fma_f32 v[48:49], v[78:79], v[62:63], v[48:49] neg_lo:[0,0,1] neg_hi:[0,0,1]
	v_mov_b32_e32 v75, v46
	v_mov_b32_e32 v89, v47
	v_pk_fma_f32 v[46:47], v[42:43], v[60:61], v[44:45] neg_lo:[0,0,1] neg_hi:[0,0,1]
	v_pk_mul_f32 v[44:45], v[90:91], v[52:53]
	v_pk_fma_f32 v[72:73], v[82:83], v[64:65], v[72:73] neg_lo:[0,0,1] neg_hi:[0,0,1]
	v_mov_b32_e32 v71, v44
	v_mov_b32_e32 v69, v45
	v_pk_add_f32 v[74:75], v[74:75], v[88:89] neg_lo:[0,1] neg_hi:[0,1]
	v_pk_fma_f32 v[76:77], v[42:43], v[54:55], v[76:77]
	v_pk_fma_f32 v[78:79], v[78:79], v[56:57], v[80:81]
	v_pk_fma_f32 v[80:81], v[82:83], v[50:51], v[86:87]
	v_pk_add_f32 v[82:83], v[70:71], v[68:69]

;     __device__ __forceinline__ void operator()(const pg8::f32x4 (&acc)[2][2][4][2], const pg8::Unit& u, int wr, int wc, int fr, int fq) const {
;     ...
;                 if (type == 1 || type == 2) {
;                     const float pos = (float)(row & 2047); const float sc = type == 2 ? 0.0625f : 1.f;
; #pragma unroll
;                     for (int e = 0; e < 8; ++e) { const float fx = __builtin_amdgcn_fractf(pos * (e < 4 ? rv0[e & 3] : rv1[e & 3]));
;                         const float c = __builtin_amdgcn_cosf(fx) * sc, s = __builtin_amdgcn_sinf(fx) * sc; const float x1 = a[e], x2 = b[e]; a[e] = x1 * c - x2 * s; b[e] = x2 * c + x1 * s; }
.LBB0_410:
	s_andn2_b64 vcc, exec, s[50:51]
	s_cbranch_vccnz .LBB0_412
	v_and_b32_e32 v26, 0x7ef, v42
	v_cvt_f32_u32_e32 v43, v26
	v_mul_f32_e32 v30, v24, v43
	v_fract_f32_e32 v31, v30
	v_cos_f32_e32 v30, v31
	v_sin_f32_e32 v32, v31
	v_mul_f32_e32 v31, v25, v43
	v_fract_f32_e32 v33, v31
	v_cos_f32_e32 v31, v33
	v_sin_f32_e32 v33, v33
	v_mul_f32_e32 v26, v22, v43
	v_fract_f32_e32 v27, v26
	v_pk_mul_f32 v[62:63], v[130:131], v[30:31] op_sel_hi:[0,1]
	v_pk_mul_f32 v[30:31], v[130:131], v[32:33] op_sel_hi:[0,1]
	v_pk_mul_f32 v[64:65], v[30:31], v[46:47]
	v_pk_mul_f32 v[32:33], v[30:31], v[40:41]
	v_mul_f32_e32 v30, v18, v43
	v_fract_f32_e32 v31, v30
	v_cos_f32_e32 v30, v31
	v_sin_f32_e32 v56, v31
	v_mul_f32_e32 v31, v19, v43
	v_fract_f32_e32 v53, v31
	v_cos_f32_e32 v31, v53
	v_sin_f32_e32 v57, v53
	v_cos_f32_e32 v26, v27
	v_sin_f32_e32 v28, v27
	v_pk_mul_f32 v[66:67], v[130:131], v[30:31] op_sel_hi:[0,1]
	v_pk_mul_f32 v[30:31], v[130:131], v[56:57] op_sel_hi:[0,1]
	v_pk_mul_f32 v[68:69], v[30:31], v[48:49]
	v_pk_mul_f32 v[56:57], v[30:31], v[34:35]
	v_mul_f32_e32 v30, v20, v43
	v_fract_f32_e32 v30, v30
	v_cos_f32_e32 v31, v30
	v_sin_f32_e32 v30, v30
	v_mul_f32_e32 v27, v23, v43
	v_fract_f32_e32 v29, v27
	v_mul_f32_e32 v31, v130, v31
	v_mul_f32_e32 v30, v130, v30
	v_mul_f32_e32 v58, v31, v52
	v_mul_f32_e32 v70, v30, v54
	v_mul_f32_e32 v52, v30, v52
	v_mul_f32_e32 v30, v21, v43
	v_mul_f32_e32 v54, v31, v54
	v_fract_f32_e32 v31, v30
	v_cos_f32_e32 v27, v29
	v_sin_f32_e32 v29, v29
	v_cos_f32_e32 v30, v31
	v_sin_f32_e32 v31, v31
	v_pk_mul_f32 v[26:27], v[130:131], v[26:27] op_sel_hi:[0,1]
	v_pk_mul_f32 v[28:29], v[130:131], v[28:29] op_sel_hi:[0,1]
	v_pk_mul_f32 v[60:61], v[28:29], v[44:45]
	v_pk_mul_f32 v[72:73], v[130:131], v[30:31] op_sel_hi:[0,1]
	v_pk_mul_f32 v[28:29], v[28:29], v[38:39]
	v_pk_mul_f32 v[30:31], v[72:73], v[50:51]
	v_pk_fma_f32 v[32:33], v[62:63], v[46:47], v[32:33] neg_lo:[0,0,1] neg_hi:[0,0,1]
	v_mov_b32_e32 v59, v30
	v_mov_b32_e32 v71, v31
	v_pk_fma_f32 v[30:31], v[26:27], v[44:45], v[28:29] neg_lo:[0,0,1] neg_hi:[0,0,1]
	v_pk_mul_f32 v[28:29], v[72:73], v[36:37]
	v_pk_fma_f32 v[56:57], v[66:67], v[48:49], v[56:57] neg_lo:[0,0,1] neg_hi:[0,0,1]
	v_mov_b32_e32 v55, v28
	v_mov_b32_e32 v53, v29
	v_pk_add_f32 v[58:59], v[58:59], v[70:71] neg_lo:[0,1] neg_hi:[0,1]
	v_pk_fma_f32 v[60:61], v[26:27], v[38:39], v[60:61]
	v_pk_fma_f32 v[62:63], v[62:63], v[40:41], v[64:65]
	v_pk_fma_f32 v[64:65], v[66:67], v[34:35], v[68:69]
	v_pk_add_f32 v[66:67], v[54:55], v[52:53]

;     __device__ __forceinline__ void operator()(const pg8::f32x4 (&acc)[2][2][4][2], const pg8::Unit& u, int wr, int wc, int fr, int fq) const {
;     ...
;                 if (type == 1 || type == 2) {
;                     const float pos = (float)(row & 2047); const float sc = type == 2 ? 0.0625f : 1.f;
; #pragma unroll
;                     for (int e = 0; e < 8; ++e) { const float fx = __builtin_amdgcn_fractf(pos * (e < 4 ? rv0[e & 3] : rv1[e & 3]));
;                         const float c = __builtin_amdgcn_cosf(fx) * sc, s = __builtin_amdgcn_sinf(fx) * sc; const float x1 = a[e], x2 = b[e]; a[e] = x1 * c - x2 * s; b[e] = x2 * c + x1 * s; }
.LBB0_437:
	s_andn2_b64 vcc, exec, s[14:15]
	s_cbranch_vccnz .LBB0_439
	v_and_b32_e32 v2, 0x7ff, v26
	v_cvt_f32_u32_e32 v27, v2
	v_mul_f32_e32 v6, v24, v27
	v_fract_f32_e32 v7, v6
	v_cos_f32_e32 v6, v7
	v_sin_f32_e32 v8, v7
	v_mul_f32_e32 v7, v25, v27
	v_fract_f32_e32 v9, v7
	v_cos_f32_e32 v7, v9
	v_sin_f32_e32 v9, v9
	v_mul_f32_e32 v2, v22, v27
	v_mul_f32_e32 v3, v23, v27
	v_pk_mul_f32 v[24:25], v[130:131], v[6:7] op_sel_hi:[0,1]
	v_pk_mul_f32 v[6:7], v[130:131], v[8:9] op_sel_hi:[0,1]
	v_mul_f32_e32 v8, v18, v27
	v_fract_f32_e32 v9, v8
	v_cos_f32_e32 v8, v9
	v_sin_f32_e32 v18, v9
	v_mul_f32_e32 v9, v19, v27
	v_fract_f32_e32 v19, v9
	v_cos_f32_e32 v9, v19
	v_sin_f32_e32 v19, v19
	v_pk_mul_f32 v[46:47], v[6:7], v[30:31]
	v_pk_mul_f32 v[40:41], v[6:7], v[16:17]
	v_fract_f32_e32 v4, v2
	v_pk_mul_f32 v[6:7], v[130:131], v[18:19] op_sel_hi:[0,1]
	v_pk_mul_f32 v[18:19], v[6:7], v[32:33]
	v_pk_mul_f32 v[42:43], v[6:7], v[10:11]
	v_mul_f32_e32 v6, v21, v27
	v_fract_f32_e32 v5, v3
	v_fract_f32_e32 v7, v6
	v_cos_f32_e32 v2, v4
	v_sin_f32_e32 v4, v4
	v_cos_f32_e32 v3, v5
	v_sin_f32_e32 v5, v5
	v_pk_mul_f32 v[48:49], v[130:131], v[8:9] op_sel_hi:[0,1]
	v_mul_f32_e32 v8, v20, v27
	v_cos_f32_e32 v6, v7
	v_sin_f32_e32 v7, v7
	v_fract_f32_e32 v8, v8
	v_cos_f32_e32 v9, v8
	v_sin_f32_e32 v8, v8
	v_pk_mul_f32 v[4:5], v[130:131], v[4:5] op_sel_hi:[0,1]
	v_pk_mul_f32 v[50:51], v[130:131], v[6:7] op_sel_hi:[0,1]
	v_pk_mul_f32 v[2:3], v[130:131], v[2:3] op_sel_hi:[0,1]
	v_pk_mul_f32 v[22:23], v[4:5], v[28:29]
	v_pk_mul_f32 v[4:5], v[4:5], v[14:15]
	v_pk_mul_f32 v[6:7], v[50:51], v[36:37]
	v_mul_f32_e32 v9, v130, v9
	v_mul_f32_e32 v8, v130, v8
	v_mov_b32_e32 v21, v6
	v_mov_b32_e32 v45, v7
	v_pk_fma_f32 v[6:7], v[2:3], v[28:29], v[4:5] neg_lo:[0,0,1] neg_hi:[0,0,1]
	v_pk_mul_f32 v[4:5], v[50:51], v[12:13]
	v_mul_f32_e32 v20, v9, v34
	v_mul_f32_e32 v44, v8, v38
	v_mul_f32_e32 v38, v9, v38
	v_mul_f32_e32 v34, v8, v34
	v_mov_b32_e32 v39, v4
	v_mov_b32_e32 v35, v5
	v_pk_fma_f32 v[8:9], v[24:25], v[30:31], v[40:41] neg_lo:[0,0,1] neg_hi:[0,0,1]
	v_pk_fma_f32 v[40:41], v[48:49], v[32:33], v[42:43] neg_lo:[0,0,1] neg_hi:[0,0,1]
	v_pk_add_f32 v[42:43], v[20:21], v[44:45] neg_lo:[0,1] neg_hi:[0,1]
	v_pk_fma_f32 v[44:45], v[2:3], v[14:15], v[22:23]
	v_pk_fma_f32 v[46:47], v[24:25], v[16:17], v[46:47]
	v_pk_fma_f32 v[48:49], v[48:49], v[10:11], v[18:19]
	v_pk_add_f32 v[50:51], v[38:39], v[34:35]

; #define LAS __attribute__((address_space(3)))
; #define GAS __attribute__((address_space(1)))
; __device__ __forceinline__ float bflo(unsigned w) { return __uint_as_float(w << 16); }
; __device__ __forceinline__ void state_unit(LAS unsigned char* lds, const bf16* RQKV, bf16* TS, unsigned* flag, int b, int h, int e, int tid) {
;     ...
;     for (int tb = 0; tb < 7; ++tb) {
; #pragma unroll
;         for (int ts = 0; ts < 4; ++ts) {
;             const int tt = 4 * tb + ts;
;             LAS unsigned char* Ks = lds + (ts & 1) * SBUF; LAS unsigned char* Vs = Ks + KB;
; #pragma unroll
;             for (int i = 0; i < 4; ++i) *(LAS u32x4*)(Ks + (srow + 16 * i) * 528 + sch * 16) = kreg[ts][i];
;             { const u32x4 v = vreg[ts]; u32x4 o; o.x = pk2(bflo(v.x) * vsc, bfhi(v.x) * vsc); o.y = pk2(bflo(v.y) * vsc, bfhi(v.y) * vsc); o.z = pk2(bflo(v.z) * vsc, bfhi(v.z) * vsc); o.w = pk2(bflo(v.w) * vsc, bfhi(v.w) * vsc);
;               *(LAS u32x4*)(Vs + vtok * VPITCH + vpc * 16) = o; }
;             __syncthreads();
;             if (tb < 6) {
; #pragma unroll
;                 for (int i = 0; i < 4; ++i) kreg[ts][i] = __builtin_nontemporal_load((const GAS u32x4*)(RK + soff + (size_t)(64 * (tt + 4) + 16 * i) * 256));
;                 vreg[ts] = *(const GAS u32x4*)(RV + voff + (size_t)(64 * (tt + 4)) * 256);
;             }
; #pragma unroll
;             for (int i = 0; i < 2; ++i)
; #pragma unroll
;                 for (int j = 0; j < 4; ++j) T[i][j] = T[i][j] * c64;
; #pragma unroll
;             for (int G = 0; G < 2; ++G) {
;                 const int trow = 32 * G + 8 * fq + (fr >> 2);
;                 bf16x8 Af[2], Bf[4];
; #pragma unroll
;                 for (int d = 0; d < 2; ++d) { LAS unsigned char* a1 = Ks + trow * 528 + (16 * (2 * w + d) + 4 * (fr & 3)) * 2; const s16x4 t1 = ldtr(a1), t2 = ldtr(a1 + 4 * 528); Af[d] = __builtin_shufflevector(t1, t2, 0, 1, 2, 3, 4, 5, 6, 7); }
; #pragma unroll
;                 for (int d = 0; d < 4; ++d) { LAS unsigned char* a1 = Vs + trow * VPITCH + (16 * d + 4 * (fr & 3)) * 2; const s16x4 t1 = ldtr(a1), t2 = ldtr(a1 + 4 * VPITCH); Bf[d] = __builtin_shufflevector(t1, t2, 0, 1, 2, 3, 4, 5, 6, 7); }
; #pragma unroll
;                 for (int i = 0; i < 2; ++i)
; #pragma unroll
;                     for (int j = 0; j < 4; ++j) T[i][j] = mfma16(Af[i], Bf[j], T[i][j]);
;             }
.LBB0_1015:
	s_waitcnt vmcnt(15)
	v_lshlrev_b32_e32 v115, 16, v26
	v_and_b32_e32 v130, 0xffff0000, v26
	v_mul_f32_e32 v115, v136, v115
	v_mul_f32_e32 v130, v136, v130
	v_cvt_pk_bf16_f32 v130, v115, v130
	v_lshlrev_b32_e32 v115, 16, v27
	v_and_b32_e32 v131, 0xffff0000, v27
	v_mul_f32_e32 v115, v136, v115
	v_mul_f32_e32 v131, v136, v131
	v_cvt_pk_bf16_f32 v131, v115, v131
	v_lshlrev_b32_e32 v115, 16, v28
	v_and_b32_e32 v132, 0xffff0000, v28
	v_mul_f32_e32 v115, v136, v115
	v_mul_f32_e32 v132, v136, v132
	v_and_b32_e32 v133, 0xffff0000, v29
	s_cmp_lg_u32 s8, 0xc0000
	v_cvt_pk_bf16_f32 v132, v115, v132
	v_lshlrev_b32_e32 v115, 16, v29
	v_mul_f32_e32 v133, v136, v133
	s_cselect_b64 s[10:11], -1, 0
	v_add_u32_e32 v145, v137, v138
	v_mul_f32_e32 v115, v136, v115
	v_cvt_pk_bf16_f32 v133, v115, v133
	ds_write_b128 v145, v[2:5]
	ds_write_b128 v145, v[6:9] offset:8448
	ds_write_b128 v145, v[14:17] offset:16896
	ds_write_b128 v145, v[18:21] offset:25344
	ds_write_b128 v139, v[130:133] offset:33792
	s_and_b64 vcc, exec, s[10:11]
	v_lshl_add_u64 v[132:133], v[128:129], 0, s[8:9]
	v_lshl_add_u64 v[130:131], v[126:127], 0, s[8:9]
	s_waitcnt lgkmcnt(0)
	s_barrier
	s_cbranch_vccz .LBB0_1017
	v_add_co_u32_e32 v2, vcc, 0x2020000, v132
	s_nop 1
	v_addc_co_u32_e32 v3, vcc, 0, v133, vcc
	v_add_co_u32_e32 v6, vcc, 0x2022000, v132
	s_nop 1
	v_addc_co_u32_e32 v7, vcc, 0, v133, vcc
	v_add_co_u32_e32 v14, vcc, 0x2024000, v132
	global_load_dwordx4 v[2:5], v[2:3], off nt
	s_nop 0
	global_load_dwordx4 v[6:9], v[6:7], off nt
	v_addc_co_u32_e32 v15, vcc, 0, v133, vcc
	v_add_co_u32_e32 v18, vcc, 0x2026000, v132
	s_nop 1
	v_addc_co_u32_e32 v19, vcc, 0, v133, vcc
	v_add_co_u32_e32 v26, vcc, 0x4020000, v130
	global_load_dwordx4 v[14:17], v[14:15], off nt
	s_nop 0
	global_load_dwordx4 v[18:21], v[18:19], off nt
	v_addc_co_u32_e32 v27, vcc, 0, v131, vcc
	global_load_dwordx4 v[26:29], v[26:27], off
.LBB0_1017:
	ds_read_b64_tr_b16 v[148:149], v140 offset:2112
	ds_read_b64_tr_b16 v[146:147], v140
	ds_read_b64_tr_b16 v[152:153], v141 offset:34368
	ds_read_b64_tr_b16 v[150:151], v141 offset:33792
	ds_read_b64_tr_b16 v[154:155], v141 offset:33824
	ds_read_b64_tr_b16 v[158:159], v141 offset:33856
	ds_read_b64_tr_b16 v[162:163], v141 offset:33888
	ds_read_b64_tr_b16 v[156:157], v141 offset:34400
	v_mov_b32_e32 v115, v114
	v_pk_mul_f32 v[108:109], v[114:115], v[108:109]
	v_pk_mul_f32 v[106:107], v[116:117], v[106:107]
	ds_read_b64_tr_b16 v[160:161], v141 offset:34432
	ds_read_b64_tr_b16 v[164:165], v141 offset:34464
	s_waitcnt lgkmcnt(2)
	v_mfma_f32_16x16x32_bf16 v[166:169], v[146:149], v[154:157], v[106:109]
	v_mul_f32_e64 v112, v114, v112
	v_mul_f32_e64 v113, v115, v113
	v_pk_mul_f32 v[110:111], v[116:117], v[110:111]
	v_pk_mul_f32 v[104:105], v[114:115], v[104:105]
	ds_read_b64_tr_b16 v[108:109], v140 offset:2144
	ds_read_b64_tr_b16 v[106:107], v140 offset:32
	v_pk_mul_f32 v[102:103], v[116:117], v[102:103]
	v_pk_mul_f32 v[100:101], v[114:115], v[100:101]
	v_pk_mul_f32 v[98:99], v[116:117], v[98:99]
	v_pk_mul_f32 v[96:97], v[114:115], v[96:97]
	v_pk_mul_f32 v[94:95], v[116:117], v[94:95]
	v_pk_mul_f32 v[92:93], v[114:115], v[92:93]
	v_pk_mul_f32 v[90:91], v[116:117], v[90:91]
	v_pk_mul_f32 v[88:89], v[114:115], v[88:89]
	v_pk_mul_f32 v[86:87], v[116:117], v[86:87]
	v_mfma_f32_16x16x32_bf16 v[110:113], v[146:149], v[150:153], v[110:113]
	v_mul_f32_e64 v84, v114, v84
	v_mul_f32_e64 v85, v115, v85
	v_pk_mul_f32 v[82:83], v[116:117], v[82:83]
	s_andn2_b64 vcc, exec, s[10:11]
	s_waitcnt lgkmcnt(3)
	v_mfma_f32_16x16x32_bf16 v[102:105], v[146:149], v[158:161], v[102:105]
	s_waitcnt lgkmcnt(2)
	v_mfma_f32_16x16x32_bf16 v[98:101], v[146:149], v[162:165], v[98:101]
	s_waitcnt lgkmcnt(0)
	v_mfma_f32_16x16x32_bf16 v[94:97], v[106:109], v[150:153], v[94:97]
	v_mfma_f32_16x16x32_bf16 v[90:93], v[106:109], v[154:157], v[90:93]
	v_mfma_f32_16x16x32_bf16 v[146:149], v[106:109], v[158:161], v[86:89]
	s_nop 2
	ds_read_b64_tr_b16 v[86:87], v140 offset:16896
	ds_read_b64_tr_b16 v[88:89], v140 offset:19008
	ds_read_b64_tr_b16 v[152:153], v141 offset:38976
	ds_read_b64_tr_b16 v[150:151], v141 offset:38400
	ds_read_b64_tr_b16 v[154:155], v141 offset:38432
	ds_read_b64_tr_b16 v[156:157], v141 offset:39008
	ds_read_b64_tr_b16 v[158:159], v141 offset:38464
	v_mfma_f32_16x16x32_bf16 v[82:85], v[106:109], v[162:165], v[82:85]
	ds_read_b64_tr_b16 v[160:161], v141 offset:39040
	ds_read_b64_tr_b16 v[162:163], v141 offset:38496
	s_waitcnt lgkmcnt(5)
	v_mfma_f32_16x16x32_bf16 v[106:109], v[86:89], v[150:153], v[110:113]
	s_waitcnt lgkmcnt(3)
	v_mfma_f32_16x16x32_bf16 v[110:113], v[86:89], v[154:157], v[166:169]
	ds_read_b64_tr_b16 v[164:165], v141 offset:39072
	s_nop 1
	ds_read_b64_tr_b16 v[168:169], v140 offset:19040
	ds_read_b64_tr_b16 v[166:167], v140 offset:16928
	s_waitcnt vmcnt(15)
	ds_write_b128 v145, v[10:13] offset:43008
	ds_write_b128 v145, v[22:25] offset:51456
	ds_write_b128 v145, v[30:33] offset:59904
	s_waitcnt lgkmcnt(7)
	v_mfma_f32_16x16x32_bf16 v[102:105], v[86:89], v[158:161], v[102:105]
	ds_write_b128 v142, v[42:45] offset:43008
	s_waitcnt lgkmcnt(6)
	v_mfma_f32_16x16x32_bf16 v[98:101], v[86:89], v[162:165], v[98:101]
	s_waitcnt lgkmcnt(4)
	v_mfma_f32_16x16x32_bf16 v[86:89], v[166:169], v[154:157], v[90:93]
	v_mfma_f32_16x16x32_bf16 v[90:93], v[166:169], v[158:161], v[146:149]
	s_nop 2
	v_lshlrev_b32_e32 v146, 16, v46
	v_and_b32_e32 v147, 0xffff0000, v46
	v_mul_f32_e32 v146, v136, v146
	v_mul_f32_e32 v147, v136, v147
	v_cvt_pk_bf16_f32 v146, v146, v147
	v_lshlrev_b32_e32 v147, 16, v47
	v_and_b32_e32 v148, 0xffff0000, v47
	v_mul_f32_e32 v147, v136, v147
	v_mul_f32_e32 v148, v136, v148
	v_cvt_pk_bf16_f32 v147, v147, v148
	v_lshlrev_b32_e32 v148, 16, v48
	v_and_b32_e32 v149, 0xffff0000, v48
	v_mul_f32_e32 v148, v136, v148
	v_mul_f32_e32 v149, v136, v149
	v_mfma_f32_16x16x32_bf16 v[94:97], v[166:169], v[150:153], v[94:97]
	v_cvt_pk_bf16_f32 v148, v148, v149
	v_lshlrev_b32_e32 v149, 16, v49
	v_mul_f32_e32 v149, v136, v149
	v_mfma_f32_16x16x32_bf16 v[82:85], v[166:169], v[162:165], v[82:85]
	v_and_b32_e32 v150, 0xffff0000, v49
	v_mul_f32_e32 v150, v136, v150
	v_cvt_pk_bf16_f32 v149, v149, v150
	ds_write_b128 v143, v[146:149]
	v_cndmask_b32_e64 v146, 0, 1, s[10:11]
	v_cmp_ne_u32_e64 s[0:1], 1, v146
	s_waitcnt lgkmcnt(0)
	s_barrier
	s_cbranch_vccnz .LBB0_1019
	v_add_co_u32_e32 v10, vcc, 0x2028000, v132
	s_nop 1
	v_addc_co_u32_e32 v11, vcc, 0, v133, vcc
	v_add_co_u32_e32 v22, vcc, 0x202a000, v132
	s_nop 1
	v_addc_co_u32_e32 v23, vcc, 0, v133, vcc
	v_add_co_u32_e32 v30, vcc, 0x202c000, v132
	global_load_dwordx4 v[10:13], v[10:11], off nt
	s_nop 0
	global_load_dwordx4 v[22:25], v[22:23], off nt
	v_addc_co_u32_e32 v31, vcc, 0, v133, vcc
	v_add_co_u32_e32 v42, vcc, 0x202e000, v132
	s_nop 1
	v_addc_co_u32_e32 v43, vcc, 0, v133, vcc
	v_add_co_u32_e32 v46, vcc, 0x4028000, v130
	global_load_dwordx4 v[30:33], v[30:31], off nt
	s_nop 0
	global_load_dwordx4 v[42:45], v[42:43], off nt
	v_addc_co_u32_e32 v47, vcc, 0, v131, vcc
	global_load_dwordx4 v[46:49], v[46:47], off
; #define LAS __attribute__((address_space(3)))
; #define GAS __attribute__((address_space(1)))
; __device__ __forceinline__ float bflo(unsigned w) { return __uint_as_float(w << 16); }
; __device__ __forceinline__ float bfhi(unsigned w) { return __uint_as_float(w & 0xffff0000u); }
; __device__ __forceinline__ void state_unit(LAS unsigned char* lds, const bf16* RQKV, bf16* TS, unsigned* flag, int b, int h, int e, int tid) {
;     ...
;         for (int ts = 0; ts < 4; ++ts) {
;             const int tt = 4 * tb + ts;
;             LAS unsigned char* Ks = lds + (ts & 1) * SBUF; LAS unsigned char* Vs = Ks + KB;
; #pragma unroll
;             for (int i = 0; i < 4; ++i) *(LAS u32x4*)(Ks + (srow + 16 * i) * 528 + sch * 16) = kreg[ts][i];
;             { const u32x4 v = vreg[ts]; u32x4 o; o.x = pk2(bflo(v.x) * vsc, bfhi(v.x) * vsc); o.y = pk2(bflo(v.y) * vsc, bfhi(v.y) * vsc); o.z = pk2(bflo(v.z) * vsc, bfhi(v.z) * vsc); o.w = pk2(bflo(v.w) * vsc, bfhi(v.w) * vsc);
;               *(LAS u32x4*)(Vs + vtok * VPITCH + vpc * 16) = o; }
;             __syncthreads();
;             if (tb < 6) {
; #pragma unroll
;                 for (int i = 0; i < 4; ++i) kreg[ts][i] = __builtin_nontemporal_load((const GAS u32x4*)(RK + soff + (size_t)(64 * (tt + 4) + 16 * i) * 256));
;                 vreg[ts] = *(const GAS u32x4*)(RV + voff + (size_t)(64 * (tt + 4)) * 256);
;             }
; #pragma unroll
;             for (int i = 0; i < 2; ++i)
; #pragma unroll
;                 for (int j = 0; j < 4; ++j) T[i][j] = T[i][j] * c64;
; #pragma unroll
;             for (int G = 0; G < 2; ++G) {
;                 const int trow = 32 * G + 8 * fq + (fr >> 2);
;                 bf16x8 Af[2], Bf[4];
; #pragma unroll
;                 for (int d = 0; d < 2; ++d) { LAS unsigned char* a1 = Ks + trow * 528 + (16 * (2 * w + d) + 4 * (fr & 3)) * 2; const s16x4 t1 = ldtr(a1), t2 = ldtr(a1 + 4 * 528); Af[d] = __builtin_shufflevector(t1, t2, 0, 1, 2, 3, 4, 5, 6, 7); }
; #pragma unroll
;                 for (int d = 0; d < 4; ++d) { LAS unsigned char* a1 = Vs + trow * VPITCH + (16 * d + 4 * (fr & 3)) * 2; const s16x4 t1 = ldtr(a1), t2 = ldtr(a1 + 4 * VPITCH); Bf[d] = __builtin_shufflevector(t1, t2, 0, 1, 2, 3, 4, 5, 6, 7); }
; #pragma unroll
;                 for (int i = 0; i < 2; ++i)
; #pragma unroll
;                     for (int j = 0; j < 4; ++j) T[i][j] = mfma16(Af[i], Bf[j], T[i][j]);
.LBB0_1019:
	ds_read_b64_tr_b16 v[148:149], v140 offset:45120
	ds_read_b64_tr_b16 v[146:147], v140 offset:43008
	ds_read_b64_tr_b16 v[152:153], v144 offset:576
	ds_read_b64_tr_b16 v[150:151], v144
	ds_read_b64_tr_b16 v[154:155], v144 offset:32
	ds_read_b64_tr_b16 v[156:157], v144 offset:608
	v_pk_mul_f32 v[112:113], v[114:115], v[112:113]
	v_pk_mul_f32 v[110:111], v[116:117], v[110:111]
	ds_read_b64_tr_b16 v[158:159], v144 offset:64
	ds_read_b64_tr_b16 v[160:161], v144 offset:640
	s_waitcnt lgkmcnt(2)
	v_mfma_f32_16x16x32_bf16 v[162:165], v[146:149], v[154:157], v[110:113]
	s_nop 2
	ds_read_b64_tr_b16 v[110:111], v144 offset:96
	ds_read_b64_tr_b16 v[112:113], v144 offset:672
	ds_read_b64_tr_b16 v[166:167], v140 offset:43040
	ds_read_b64_tr_b16 v[168:169], v140 offset:45152
	v_pk_mul_f32 v[108:109], v[114:115], v[108:109]
	v_pk_mul_f32 v[106:107], v[116:117], v[106:107]
	v_pk_mul_f32 v[104:105], v[114:115], v[104:105]
	v_pk_mul_f32 v[102:103], v[116:117], v[102:103]
	v_pk_mul_f32 v[96:97], v[114:115], v[96:97]
	v_pk_mul_f32 v[94:95], v[116:117], v[94:95]
	v_pk_mul_f32 v[88:89], v[114:115], v[88:89]
	v_pk_mul_f32 v[86:87], v[116:117], v[86:87]
	v_pk_mul_f32 v[92:93], v[114:115], v[92:93]
	v_pk_mul_f32 v[90:91], v[116:117], v[90:91]
	v_pk_mul_f32 v[84:85], v[114:115], v[84:85]
	v_pk_mul_f32 v[82:83], v[116:117], v[82:83]
	v_mfma_f32_16x16x32_bf16 v[106:109], v[146:149], v[150:153], v[106:109]
	v_mul_f32_e64 v100, v114, v100
	v_mul_f32_e64 v101, v115, v101
	v_pk_mul_f32 v[98:99], v[116:117], v[98:99]
	s_and_b64 vcc, exec, s[0:1]
	s_waitcnt lgkmcnt(4)
	v_mfma_f32_16x16x32_bf16 v[102:105], v[146:149], v[158:161], v[102:105]
	s_waitcnt lgkmcnt(0)
	v_mfma_f32_16x16x32_bf16 v[94:97], v[166:169], v[150:153], v[94:97]
	ds_read_b64_tr_b16 v[150:151], v140 offset:59904
	ds_read_b64_tr_b16 v[152:153], v140 offset:62016
	v_mfma_f32_16x16x32_bf16 v[86:89], v[166:169], v[154:157], v[86:89]
	v_mfma_f32_16x16x32_bf16 v[90:93], v[166:169], v[158:161], v[90:93]
	v_mfma_f32_16x16x32_bf16 v[154:157], v[166:169], v[110:113], v[82:85]
	s_nop 2
	ds_read_b64_tr_b16 v[82:83], v144 offset:4608
	ds_read_b64_tr_b16 v[84:85], v144 offset:5184
	ds_read_b64_tr_b16 v[158:159], v144 offset:4640
	ds_read_b64_tr_b16 v[160:161], v144 offset:5216
	ds_read_b64_tr_b16 v[166:167], v144 offset:4672
	v_mfma_f32_16x16x32_bf16 v[146:149], v[146:149], v[110:113], v[98:101]
	s_waitcnt lgkmcnt(3)
	v_mfma_f32_16x16x32_bf16 v[110:113], v[150:153], v[82:85], v[106:109]
	s_waitcnt lgkmcnt(1)
	v_mfma_f32_16x16x32_bf16 v[106:109], v[150:153], v[158:161], v[162:165]
	ds_read_b64_tr_b16 v[168:169], v144 offset:5248
	s_nop 1
	ds_read_b64_tr_b16 v[162:163], v144 offset:4704
	ds_read_b64_tr_b16 v[164:165], v144 offset:5280
	ds_read_b64_tr_b16 v[170:171], v140 offset:59936
	ds_read_b64_tr_b16 v[172:173], v140 offset:62048
	s_waitcnt lgkmcnt(4)
	v_mfma_f32_16x16x32_bf16 v[98:101], v[150:153], v[166:169], v[102:105]
	s_waitcnt vmcnt(13)
	ds_write_b128 v145, v[34:37]
	ds_write_b128 v145, v[38:41] offset:8448
	ds_write_b128 v145, v[54:57] offset:16896
	ds_write_b128 v145, v[58:61] offset:25344
	s_waitcnt lgkmcnt(6)
	v_mfma_f32_16x16x32_bf16 v[102:105], v[150:153], v[162:165], v[146:149]
	s_waitcnt lgkmcnt(4)
	v_mfma_f32_16x16x32_bf16 v[82:85], v[170:173], v[82:85], v[94:97]
	s_nop 0
	v_and_b32_e32 v146, 0xffff0000, v66
	v_mul_f32_e32 v146, v136, v146
	v_and_b32_e32 v147, 0xffff0000, v67
	v_mfma_f32_16x16x32_bf16 v[94:97], v[170:173], v[166:169], v[90:93]
	v_mul_f32_e32 v147, v136, v147
	v_and_b32_e32 v148, 0xffff0000, v68
	v_mul_f32_e32 v148, v136, v148
	v_lshlrev_b32_e32 v90, 16, v66
	v_mul_f32_e32 v115, v136, v90
	v_cvt_pk_bf16_f32 v146, v115, v146
	v_lshlrev_b32_e32 v115, 16, v67
	v_mfma_f32_16x16x32_bf16 v[86:89], v[170:173], v[158:161], v[86:89]
	v_mul_f32_e32 v115, v136, v115
	v_cvt_pk_bf16_f32 v147, v115, v147
	v_lshlrev_b32_e32 v115, 16, v68
	v_mfma_f32_16x16x32_bf16 v[90:93], v[170:173], v[162:165], v[154:157]
	v_mul_f32_e32 v115, v136, v115
	v_and_b32_e32 v149, 0xffff0000, v69
	v_cvt_pk_bf16_f32 v148, v115, v148
	v_lshlrev_b32_e32 v115, 16, v69
	v_mul_f32_e32 v149, v136, v149
	v_mul_f32_e32 v115, v136, v115
	v_cvt_pk_bf16_f32 v149, v115, v149
	ds_write_b128 v139, v[146:149] offset:33792
	s_waitcnt lgkmcnt(0)
	s_barrier
	s_cbranch_vccnz .LBB0_1021
	v_add_co_u32_e32 v34, vcc, 0x2030000, v132
	s_nop 1
	v_addc_co_u32_e32 v35, vcc, 0, v133, vcc
	v_add_co_u32_e32 v38, vcc, 0x2032000, v132
	s_nop 1
	v_addc_co_u32_e32 v39, vcc, 0, v133, vcc
	v_add_co_u32_e32 v54, vcc, 0x2034000, v132
	global_load_dwordx4 v[34:37], v[34:35], off nt
	s_nop 0
	global_load_dwordx4 v[38:41], v[38:39], off nt
	v_addc_co_u32_e32 v55, vcc, 0, v133, vcc
	v_add_co_u32_e32 v58, vcc, 0x2036000, v132
	s_nop 1
	v_addc_co_u32_e32 v59, vcc, 0, v133, vcc
	v_add_co_u32_e32 v66, vcc, 0x4030000, v130
	global_load_dwordx4 v[54:57], v[54:55], off nt
	s_nop 0
	global_load_dwordx4 v[58:61], v[58:59], off nt
	v_addc_co_u32_e32 v67, vcc, 0, v131, vcc
	global_load_dwordx4 v[66:69], v[66:67], off
; #define LAS __attribute__((address_space(3)))
; #define GAS __attribute__((address_space(1)))
; __device__ __forceinline__ float bflo(unsigned w) { return __uint_as_float(w << 16); }
; __device__ __forceinline__ float bfhi(unsigned w) { return __uint_as_float(w & 0xffff0000u); }
; __device__ __forceinline__ void state_unit(LAS unsigned char* lds, const bf16* RQKV, bf16* TS, unsigned* flag, int b, int h, int e, int tid) {
;     ...
;         for (int ts = 0; ts < 4; ++ts) {
;             const int tt = 4 * tb + ts;
;             LAS unsigned char* Ks = lds + (ts & 1) * SBUF; LAS unsigned char* Vs = Ks + KB;
; #pragma unroll
;             for (int i = 0; i < 4; ++i) *(LAS u32x4*)(Ks + (srow + 16 * i) * 528 + sch * 16) = kreg[ts][i];
;             { const u32x4 v = vreg[ts]; u32x4 o; o.x = pk2(bflo(v.x) * vsc, bfhi(v.x) * vsc); o.y = pk2(bflo(v.y) * vsc, bfhi(v.y) * vsc); o.z = pk2(bflo(v.z) * vsc, bfhi(v.z) * vsc); o.w = pk2(bflo(v.w) * vsc, bfhi(v.w) * vsc);
;               *(LAS u32x4*)(Vs + vtok * VPITCH + vpc * 16) = o; }
;             __syncthreads();
;             if (tb < 6) {
; #pragma unroll
;                 for (int i = 0; i < 4; ++i) kreg[ts][i] = __builtin_nontemporal_load((const GAS u32x4*)(RK + soff + (size_t)(64 * (tt + 4) + 16 * i) * 256));
;                 vreg[ts] = *(const GAS u32x4*)(RV + voff + (size_t)(64 * (tt + 4)) * 256);
;             }
; #pragma unroll
;             for (int i = 0; i < 2; ++i)
; #pragma unroll
;                 for (int j = 0; j < 4; ++j) T[i][j] = T[i][j] * c64;
; #pragma unroll
;             for (int G = 0; G < 2; ++G) {
;                 const int trow = 32 * G + 8 * fq + (fr >> 2);
;                 bf16x8 Af[2], Bf[4];
; #pragma unroll
;                 for (int d = 0; d < 2; ++d) { LAS unsigned char* a1 = Ks + trow * 528 + (16 * (2 * w + d) + 4 * (fr & 3)) * 2; const s16x4 t1 = ldtr(a1), t2 = ldtr(a1 + 4 * 528); Af[d] = __builtin_shufflevector(t1, t2, 0, 1, 2, 3, 4, 5, 6, 7); }
; #pragma unroll
;                 for (int d = 0; d < 4; ++d) { LAS unsigned char* a1 = Vs + trow * VPITCH + (16 * d + 4 * (fr & 3)) * 2; const s16x4 t1 = ldtr(a1), t2 = ldtr(a1 + 4 * VPITCH); Bf[d] = __builtin_shufflevector(t1, t2, 0, 1, 2, 3, 4, 5, 6, 7); }
; #pragma unroll
;                 for (int i = 0; i < 2; ++i)
; #pragma unroll
;                     for (int j = 0; j < 4; ++j) T[i][j] = mfma16(Af[i], Bf[j], T[i][j]);
.LBB0_1021:
	ds_read_b64_tr_b16 v[148:149], v140 offset:2112
	ds_read_b64_tr_b16 v[146:147], v140
	ds_read_b64_tr_b16 v[152:153], v141 offset:34368
	ds_read_b64_tr_b16 v[150:151], v141 offset:33792
	ds_read_b64_tr_b16 v[154:155], v141 offset:33824
	ds_read_b64_tr_b16 v[158:159], v141 offset:33856
	ds_read_b64_tr_b16 v[162:163], v141 offset:33888
	ds_read_b64_tr_b16 v[156:157], v141 offset:34400
	ds_read_b64_tr_b16 v[160:161], v141 offset:34432
	ds_read_b64_tr_b16 v[164:165], v141 offset:34464
	ds_read_b64_tr_b16 v[168:169], v140 offset:2144
	ds_read_b64_tr_b16 v[166:167], v140 offset:32
	v_mov_b32_e32 v115, v114
	v_pk_mul_f32 v[112:113], v[114:115], v[112:113]
	v_pk_mul_f32 v[110:111], v[116:117], v[110:111]
	v_pk_mul_f32 v[108:109], v[114:115], v[108:109]
	v_pk_mul_f32 v[106:107], v[116:117], v[106:107]
	v_pk_mul_f32 v[100:101], v[114:115], v[100:101]
	v_pk_mul_f32 v[98:99], v[116:117], v[98:99]
	v_pk_mul_f32 v[104:105], v[114:115], v[104:105]
	v_pk_mul_f32 v[102:103], v[116:117], v[102:103]
	v_pk_mul_f32 v[84:85], v[114:115], v[84:85]
	v_pk_mul_f32 v[82:83], v[116:117], v[82:83]
	v_pk_mul_f32 v[88:89], v[114:115], v[88:89]
	v_pk_mul_f32 v[86:87], v[116:117], v[86:87]
	v_pk_mul_f32 v[96:97], v[114:115], v[96:97]
	v_pk_mul_f32 v[94:95], v[116:117], v[94:95]
	v_pk_mul_f32 v[92:93], v[114:115], v[92:93]
	v_pk_mul_f32 v[90:91], v[116:117], v[90:91]
	s_waitcnt lgkmcnt(8)
	v_mfma_f32_16x16x32_bf16 v[110:113], v[146:149], v[150:153], v[110:113]
	s_and_b64 vcc, exec, s[0:1]
	s_waitcnt lgkmcnt(4)
	v_mfma_f32_16x16x32_bf16 v[106:109], v[146:149], v[154:157], v[106:109]
	s_waitcnt lgkmcnt(3)
	v_mfma_f32_16x16x32_bf16 v[98:101], v[146:149], v[158:161], v[98:101]
	s_waitcnt lgkmcnt(2)
	v_mfma_f32_16x16x32_bf16 v[102:105], v[146:149], v[162:165], v[102:105]
	s_waitcnt lgkmcnt(0)
	v_mfma_f32_16x16x32_bf16 v[82:85], v[166:169], v[150:153], v[82:85]
	v_mfma_f32_16x16x32_bf16 v[86:89], v[166:169], v[154:157], v[86:89]
	v_mfma_f32_16x16x32_bf16 v[146:149], v[166:169], v[158:161], v[94:97]
	s_nop 2
	ds_read_b64_tr_b16 v[94:95], v140 offset:16896
	ds_read_b64_tr_b16 v[96:97], v140 offset:19008
	v_mfma_f32_16x16x32_bf16 v[150:153], v[166:169], v[162:165], v[90:93]
	s_nop 2
	ds_read_b64_tr_b16 v[92:93], v141 offset:38976
	ds_read_b64_tr_b16 v[90:91], v141 offset:38400
	ds_read_b64_tr_b16 v[154:155], v141 offset:38432
	ds_read_b64_tr_b16 v[156:157], v141 offset:39008
	ds_read_b64_tr_b16 v[158:159], v141 offset:38464
	ds_read_b64_tr_b16 v[160:161], v141 offset:39040
	ds_read_b64_tr_b16 v[162:163], v141 offset:38496
	ds_read_b64_tr_b16 v[164:165], v141 offset:39072
	ds_read_b64_tr_b16 v[168:169], v140 offset:19040
	ds_read_b64_tr_b16 v[166:167], v140 offset:16928
	s_waitcnt lgkmcnt(8)
	v_mfma_f32_16x16x32_bf16 v[110:113], v[94:97], v[90:93], v[110:113]
	s_waitcnt vmcnt(8)
	ds_write_b128 v145, v[50:53] offset:43008
	ds_write_b128 v145, v[62:65] offset:51456
	ds_write_b128 v145, v[70:73] offset:59904
	ds_write_b128 v142, v[74:77] offset:43008
	s_waitcnt lgkmcnt(10)
	v_mfma_f32_16x16x32_bf16 v[106:109], v[94:97], v[154:157], v[106:109]
	s_waitcnt lgkmcnt(8)
	v_mfma_f32_16x16x32_bf16 v[98:101], v[94:97], v[158:161], v[98:101]
	s_waitcnt lgkmcnt(6)
	v_mfma_f32_16x16x32_bf16 v[102:105], v[94:97], v[162:165], v[102:105]
	s_waitcnt lgkmcnt(4)
	v_mfma_f32_16x16x32_bf16 v[94:97], v[166:169], v[90:93], v[82:85]
	v_mfma_f32_16x16x32_bf16 v[82:85], v[166:169], v[154:157], v[86:89]
	v_mfma_f32_16x16x32_bf16 v[90:93], v[166:169], v[158:161], v[146:149]
	s_nop 1
	v_lshlrev_b32_e32 v86, 16, v78
	v_mul_f32_e32 v145, v136, v86
	v_and_b32_e32 v146, 0xffff0000, v78
	v_mul_f32_e32 v146, v136, v146
	v_cvt_pk_bf16_f32 v146, v145, v146
	v_lshlrev_b32_e32 v145, 16, v79
	v_and_b32_e32 v147, 0xffff0000, v79
	v_mfma_f32_16x16x32_bf16 v[86:89], v[166:169], v[162:165], v[150:153]
	v_mul_f32_e32 v145, v136, v145
	v_mul_f32_e32 v147, v136, v147
	v_cvt_pk_bf16_f32 v147, v145, v147
	v_lshlrev_b32_e32 v145, 16, v80
	v_and_b32_e32 v148, 0xffff0000, v80
	v_mul_f32_e32 v145, v136, v145
	v_mul_f32_e32 v148, v136, v148
	v_and_b32_e32 v149, 0xffff0000, v81
	v_cvt_pk_bf16_f32 v148, v145, v148
	v_lshlrev_b32_e32 v145, 16, v81
	v_mul_f32_e32 v149, v136, v149
	v_mul_f32_e32 v145, v136, v145
	v_cvt_pk_bf16_f32 v149, v145, v149
	ds_write_b128 v143, v[146:149]
	s_waitcnt lgkmcnt(0)
	s_barrier
	s_cbranch_vccnz .LBB0_1014
	v_add_co_u32_e32 v50, vcc, 0x2038000, v132
	s_nop 1
	v_addc_co_u32_e32 v51, vcc, 0, v133, vcc
	v_add_co_u32_e32 v62, vcc, 0x203a000, v132
	s_nop 1
	v_addc_co_u32_e32 v63, vcc, 0, v133, vcc
	v_add_co_u32_e32 v70, vcc, 0x203c000, v132
	global_load_dwordx4 v[50:53], v[50:51], off nt
	s_nop 0
	global_load_dwordx4 v[62:65], v[62:63], off nt
	v_addc_co_u32_e32 v71, vcc, 0, v133, vcc
	v_add_co_u32_e32 v74, vcc, 0x203e000, v132
	s_nop 1
	v_addc_co_u32_e32 v75, vcc, 0, v133, vcc
	v_add_co_u32_e32 v78, vcc, 0x4038000, v130
	global_load_dwordx4 v[70:73], v[70:71], off nt
	s_nop 0
	global_load_dwordx4 v[74:77], v[74:75], off nt
	v_addc_co_u32_e32 v79, vcc, 0, v131, vcc
	global_load_dwordx4 v[78:81], v[78:79], off
	s_branch .LBB0_1014
